# DA MFMA block: every transposed V operand read issued two k-steps (8 MFMAs) ahead as soon as its registers are free (was one k-step), K fragments during PV k2; plus MLA block reorder
# baseline (speedup 1.0000x reference)
.LBB0_599:
	s_barrier
	s_setprio 3
	ds_read_b64_tr_b16 v[194:195], v238 offset:0
	ds_read_b64_tr_b16 v[196:197], v238 offset:0x800
	ds_read_b64_tr_b16 v[198:199], v238 offset:0x200
	ds_read_b64_tr_b16 v[200:201], v238 offset:0xa00
	ds_read_b64_tr_b16 v[202:203], v238 offset:0x400
	ds_read_b64_tr_b16 v[204:205], v238 offset:0xc00
	ds_read_b64_tr_b16 v[206:207], v238 offset:0x600
	ds_read_b64_tr_b16 v[208:209], v238 offset:0xe00
	ds_read_b64_tr_b16 v[210:211], v238 offset:0x1000
	ds_read_b64_tr_b16 v[212:213], v238 offset:0x1800
	ds_read_b64_tr_b16 v[214:215], v238 offset:0x1200
	ds_read_b64_tr_b16 v[216:217], v238 offset:0x1a00
	ds_read_b64_tr_b16 v[218:219], v238 offset:0x1400
	ds_read_b64_tr_b16 v[220:221], v238 offset:0x1c00
	s_waitcnt lgkmcnt(12)
	v_mfma_f32_32x32x16_bf16 v[50:65], v[142:145], v[194:197], v[50:65]
	v_cvt_pk_bf16_f32 v138, v106, v107
	ds_read_b64_tr_b16 v[222:223], v238 offset:0x1600
	ds_read_b64_tr_b16 v[224:225], v238 offset:0x1e00
	s_waitcnt lgkmcnt(12)
	v_mfma_f32_32x32x16_bf16 v[34:49], v[142:145], v[198:201], v[34:49]
	v_cvt_pk_bf16_f32 v139, v108, v109
	ds_read_b64_tr_b16 v[194:195], v238 offset:0x2000
	ds_read_b64_tr_b16 v[196:197], v238 offset:0x2800
	s_waitcnt lgkmcnt(12)
	v_mfma_f32_32x32x16_bf16 v[18:33], v[142:145], v[202:205], v[18:33]
	v_cvt_pk_bf16_f32 v140, v110, v111
	ds_read_b64_tr_b16 v[198:199], v238 offset:0x2200
	ds_read_b64_tr_b16 v[200:201], v238 offset:0x2a00
	s_waitcnt lgkmcnt(12)
	v_mfma_f32_32x32x16_bf16 v[2:17], v[142:145], v[206:209], v[2:17]
	v_cvt_pk_bf16_f32 v141, v112, v113
	ds_read_b64_tr_b16 v[202:203], v238 offset:0x2400
	ds_read_b64_tr_b16 v[204:205], v238 offset:0x2c00
	v_mfma_f32_16x16x32_bf16 v[244:247], v[142:145], v[248:251], v[244:247]
	s_waitcnt lgkmcnt(12)
	v_mfma_f32_32x32x16_bf16 v[50:65], v[138:141], v[210:213], v[50:65]
	v_cvt_pk_bf16_f32 v134, v82, v83
	ds_read_b64_tr_b16 v[206:207], v238 offset:0x2600
	ds_read_b64_tr_b16 v[208:209], v238 offset:0x2e00
	s_waitcnt lgkmcnt(12)
	v_mfma_f32_32x32x16_bf16 v[34:49], v[138:141], v[214:217], v[34:49]
	v_cvt_pk_bf16_f32 v135, v84, v85
	ds_read_b64_tr_b16 v[210:211], v238 offset:0x3000
	ds_read_b64_tr_b16 v[212:213], v238 offset:0x3800
	s_waitcnt lgkmcnt(12)
	v_mfma_f32_32x32x16_bf16 v[18:33], v[138:141], v[218:221], v[18:33]
	v_cvt_pk_bf16_f32 v136, v86, v87
	ds_read_b64_tr_b16 v[214:215], v238 offset:0x3200
	ds_read_b64_tr_b16 v[216:217], v238 offset:0x3a00
	s_waitcnt lgkmcnt(12)
	v_mfma_f32_32x32x16_bf16 v[2:17], v[138:141], v[222:225], v[2:17]
	v_cvt_pk_bf16_f32 v137, v88, v89
	ds_read_b64_tr_b16 v[218:219], v238 offset:0x3400
	ds_read_b64_tr_b16 v[220:221], v238 offset:0x3c00
	v_mfma_f32_16x16x32_bf16 v[244:247], v[138:141], v[248:251], v[244:247]
	s_waitcnt lgkmcnt(12)
	v_mfma_f32_32x32x16_bf16 v[50:65], v[134:137], v[194:197], v[50:65]
	v_cvt_pk_bf16_f32 v130, v90, v91
	ds_read_b64_tr_b16 v[222:223], v238 offset:0x3600
	ds_read_b64_tr_b16 v[224:225], v238 offset:0x3e00
	ds_read_b128 v[226:229], v188 offset:45056
	s_waitcnt lgkmcnt(13)
	v_mfma_f32_32x32x16_bf16 v[34:49], v[134:137], v[198:201], v[34:49]
	v_cvt_pk_bf16_f32 v131, v92, v93
	ds_read_b128 v[230:233], v189 offset:40960
	ds_read_b128 v[194:197], v190 offset:40960
	s_waitcnt lgkmcnt(13)
	v_mfma_f32_32x32x16_bf16 v[18:33], v[134:137], v[202:205], v[18:33]
	v_cvt_pk_bf16_f32 v132, v94, v95
	ds_read_b128 v[234:237], v189 offset:45056
	ds_read_b128 v[198:201], v190 offset:45056
	s_waitcnt lgkmcnt(13)
	v_mfma_f32_32x32x16_bf16 v[2:17], v[134:137], v[206:209], v[2:17]
	v_cvt_pk_bf16_f32 v133, v96, v97
	ds_read_b128 v[82:85], v188 offset:40960
	ds_read_b128 v[202:205], v191 offset:40960
	v_mfma_f32_16x16x32_bf16 v[244:247], v[134:137], v[248:251], v[244:247]
	s_waitcnt lgkmcnt(13)
	v_mfma_f32_32x32x16_bf16 v[50:65], v[130:133], v[210:213], v[50:65]
	ds_read_b128 v[206:209], v191 offset:45056
	s_waitcnt lgkmcnt(12)
	v_mfma_f32_32x32x16_bf16 v[34:49], v[130:133], v[214:217], v[34:49]
	s_waitcnt lgkmcnt(10)
	v_mfma_f32_32x32x16_bf16 v[18:33], v[130:133], v[218:221], v[18:33]
	s_waitcnt lgkmcnt(8)
	v_mfma_f32_32x32x16_bf16 v[2:17], v[130:133], v[222:225], v[2:17]
	v_mfma_f32_16x16x32_bf16 v[244:247], v[130:133], v[248:251], v[244:247]
	s_waitcnt lgkmcnt(2)
	v_mfma_f32_32x32x16_bf16 v[98:113], v[82:85], v[126:129], v[66:81]
	v_mfma_f32_32x32x16_bf16 v[82:97], v[226:229], v[126:129], v[66:81]
	v_mfma_f32_32x32x16_bf16 v[98:113], v[230:233], v[122:125], v[98:113]
	v_mfma_f32_32x32x16_bf16 v[82:97], v[234:237], v[122:125], v[82:97]
	v_mfma_f32_32x32x16_bf16 v[98:113], v[194:197], v[118:121], v[98:113]
	v_mfma_f32_32x32x16_bf16 v[82:97], v[198:201], v[118:121], v[82:97]
	s_waitcnt lgkmcnt(1)
	v_mfma_f32_32x32x16_bf16 v[98:113], v[202:205], v[114:117], v[98:113]
	s_waitcnt lgkmcnt(0)
	v_mfma_f32_32x32x16_bf16 v[82:97], v[206:209], v[114:117], v[82:97]

.LBB0_612:
	s_barrier
	s_setprio 3
	v_add_u32_e32 v197, s75, v193
	ds_read_b64_tr_b16 v[198:199], v197 offset:0
	ds_read_b64_tr_b16 v[200:201], v197 offset:0x800
	ds_read_b64_tr_b16 v[202:203], v197 offset:0x200
	ds_read_b64_tr_b16 v[204:205], v197 offset:0xa00
	ds_read_b64_tr_b16 v[206:207], v197 offset:0x400
	ds_read_b64_tr_b16 v[208:209], v197 offset:0xc00
	ds_read_b64_tr_b16 v[210:211], v197 offset:0x600
	ds_read_b64_tr_b16 v[212:213], v197 offset:0xe00
	ds_read_b64_tr_b16 v[214:215], v197 offset:0x1000
	ds_read_b64_tr_b16 v[216:217], v197 offset:0x1800
	ds_read_b64_tr_b16 v[218:219], v197 offset:0x1200
	ds_read_b64_tr_b16 v[220:221], v197 offset:0x1a00
	ds_read_b64_tr_b16 v[222:223], v197 offset:0x1400
	ds_read_b64_tr_b16 v[224:225], v197 offset:0x1c00
	s_waitcnt lgkmcnt(12)
	v_mfma_f32_32x32x16_bf16 v[50:65], v[142:145], v[198:201], v[50:65]
	v_cvt_pk_bf16_f32 v138, v106, v107
	ds_read_b64_tr_b16 v[226:227], v197 offset:0x1600
	ds_read_b64_tr_b16 v[228:229], v197 offset:0x1e00
	s_waitcnt lgkmcnt(12)
	v_mfma_f32_32x32x16_bf16 v[34:49], v[142:145], v[202:205], v[34:49]
	v_cvt_pk_bf16_f32 v139, v108, v109
	ds_read_b64_tr_b16 v[198:199], v197 offset:0x2000
	ds_read_b64_tr_b16 v[200:201], v197 offset:0x2800
	s_waitcnt lgkmcnt(12)
	v_mfma_f32_32x32x16_bf16 v[18:33], v[142:145], v[206:209], v[18:33]
	v_cvt_pk_bf16_f32 v140, v110, v111
	ds_read_b64_tr_b16 v[202:203], v197 offset:0x2200
	ds_read_b64_tr_b16 v[204:205], v197 offset:0x2a00
	s_waitcnt lgkmcnt(12)
	v_mfma_f32_32x32x16_bf16 v[2:17], v[142:145], v[210:213], v[2:17]
	v_cvt_pk_bf16_f32 v141, v112, v113
	ds_read_b64_tr_b16 v[206:207], v197 offset:0x2400
	ds_read_b64_tr_b16 v[208:209], v197 offset:0x2c00
	v_mfma_f32_16x16x32_bf16 v[244:247], v[142:145], v[248:251], v[244:247]
	s_waitcnt lgkmcnt(12)
	v_mfma_f32_32x32x16_bf16 v[50:65], v[138:141], v[214:217], v[50:65]
	v_cvt_pk_bf16_f32 v134, v82, v83
	ds_read_b64_tr_b16 v[210:211], v197 offset:0x2600
	ds_read_b64_tr_b16 v[212:213], v197 offset:0x2e00
	s_waitcnt lgkmcnt(12)
	v_mfma_f32_32x32x16_bf16 v[34:49], v[138:141], v[218:221], v[34:49]
	v_cvt_pk_bf16_f32 v135, v84, v85
	ds_read_b64_tr_b16 v[214:215], v197 offset:0x3000
	ds_read_b64_tr_b16 v[216:217], v197 offset:0x3800
	s_waitcnt lgkmcnt(12)
	v_mfma_f32_32x32x16_bf16 v[18:33], v[138:141], v[222:225], v[18:33]
	v_cvt_pk_bf16_f32 v136, v86, v87
	ds_read_b64_tr_b16 v[218:219], v197 offset:0x3200
	ds_read_b64_tr_b16 v[220:221], v197 offset:0x3a00
	s_waitcnt lgkmcnt(12)
	v_mfma_f32_32x32x16_bf16 v[2:17], v[138:141], v[226:229], v[2:17]
	v_cvt_pk_bf16_f32 v137, v88, v89
	ds_read_b64_tr_b16 v[222:223], v197 offset:0x3400
	ds_read_b64_tr_b16 v[224:225], v197 offset:0x3c00
	v_mfma_f32_16x16x32_bf16 v[244:247], v[138:141], v[248:251], v[244:247]
	s_waitcnt lgkmcnt(12)
	v_mfma_f32_32x32x16_bf16 v[50:65], v[134:137], v[198:201], v[50:65]
	v_cvt_pk_bf16_f32 v130, v90, v91
	ds_read_b64_tr_b16 v[226:227], v197 offset:0x3600
	ds_read_b64_tr_b16 v[228:229], v197 offset:0x3e00
	ds_read_b128 v[230:233], v188 offset:36864
	s_waitcnt lgkmcnt(13)
	v_mfma_f32_32x32x16_bf16 v[34:49], v[134:137], v[202:205], v[34:49]
	v_cvt_pk_bf16_f32 v131, v92, v93
	ds_read_b128 v[234:237], v189 offset:32768
	ds_read_b128 v[198:201], v190 offset:32768
	s_waitcnt lgkmcnt(13)
	v_mfma_f32_32x32x16_bf16 v[18:33], v[134:137], v[206:209], v[18:33]
	v_cvt_pk_bf16_f32 v132, v94, v95
	ds_read_b128 v[238:241], v189 offset:36864
	ds_read_b128 v[202:205], v190 offset:36864
	s_waitcnt lgkmcnt(13)
	v_mfma_f32_32x32x16_bf16 v[2:17], v[134:137], v[210:213], v[2:17]
	v_cvt_pk_bf16_f32 v133, v96, v97
	ds_read_b128 v[82:85], v188 offset:32768
	ds_read_b128 v[206:209], v191 offset:32768
	v_mfma_f32_16x16x32_bf16 v[244:247], v[134:137], v[248:251], v[244:247]
	s_waitcnt lgkmcnt(13)
	v_mfma_f32_32x32x16_bf16 v[50:65], v[130:133], v[214:217], v[50:65]
	ds_read_b128 v[210:213], v191 offset:36864
	s_waitcnt lgkmcnt(12)
	v_mfma_f32_32x32x16_bf16 v[34:49], v[130:133], v[218:221], v[34:49]
	s_waitcnt lgkmcnt(10)
	v_mfma_f32_32x32x16_bf16 v[18:33], v[130:133], v[222:225], v[18:33]
	s_waitcnt lgkmcnt(8)
	v_mfma_f32_32x32x16_bf16 v[2:17], v[130:133], v[226:229], v[2:17]
	v_mfma_f32_16x16x32_bf16 v[244:247], v[130:133], v[248:251], v[244:247]
	s_waitcnt lgkmcnt(2)
	v_mfma_f32_32x32x16_bf16 v[98:113], v[82:85], v[126:129], v[66:81]
	v_mfma_f32_32x32x16_bf16 v[82:97], v[230:233], v[126:129], v[66:81]
	v_mfma_f32_32x32x16_bf16 v[98:113], v[234:237], v[122:125], v[98:113]
	v_mfma_f32_32x32x16_bf16 v[82:97], v[238:241], v[122:125], v[82:97]
	v_mfma_f32_32x32x16_bf16 v[98:113], v[198:201], v[118:121], v[98:113]
	v_mfma_f32_32x32x16_bf16 v[82:97], v[202:205], v[118:121], v[82:97]
	s_waitcnt lgkmcnt(1)
	v_mfma_f32_32x32x16_bf16 v[98:113], v[206:209], v[114:117], v[98:113]
	s_waitcnt lgkmcnt(0)
	v_mfma_f32_32x32x16_bf16 v[82:97], v[210:213], v[114:117], v[82:97]
	s_and_b64 vcc, exec, s[6:7]
	s_cbranch_vccnz .LBB0_614
	s_waitcnt vmcnt(1)
